# phase 9 (final residual + norm rows): gain vectors hoisted out of the row loop, all four x chunks of a row fetched at the loop top instead of one chunk after each store
# speedup vs baseline: 1.0071x; 1.0071x over previous
; DI void phase9(const Params& p) {
;     const int lane = VTID & 63, w = VTID >> 6;
;     const float* x = p.in[0]; const float* g1 = p.in[15]; const float* g2 = p.in[20];
;     const bf16_t* MIX = (const bf16_t*)(p.ws + OFF_MIX);
;     const bf16_t* F = (const bf16_t*)(p.ws + OFF_O);
;     const float* RSTD = (const float*)(p.ws + OFF_GATES);
;     for (int row = VBLK * 4 + w; row < T; row += VGRID * 4) {
;     ...
;             const f32x4 ga = *(const f32x4*)(g1 + i * 256 + lane * 4);
;             const f32x4 gb = *(const f32x4*)(g2 + i * 256 + lane * 4);
.LBB0_904:
	s_cmp_gt_i32 s90, 9
	s_cselect_b64 s[0:1], -1, 0
	s_cmp_lt_i32 s91, 10
	s_cselect_b64 s[2:3], -1, 0
	s_or_b64 s[0:1], s[0:1], s[2:3]
	s_and_b64 vcc, exec, s[0:1]
	s_cbranch_vccnz .LBB0_958
	v_and_b32_e32 v14, 0x3ff, v0
	v_readlane_b32 s0, v238, 0
	v_bfe_u32 v0, v14, 6, 2
	s_lshl_b32 s0, s0, 3
	v_or3_b32 v0, v150, s0, v0
	s_mov_b32 s0, 0x8000
	v_cmp_gt_i32_e32 vcc, s0, v0
	s_and_saveexec_b64 s[0:1], vcc
	v_readlane_b32 s16, v238, 15
	v_readlane_b32 s17, v238, 16
	v_readlane_b32 s18, v238, 17
	v_readlane_b32 s19, v238, 18
	v_readlane_b32 s20, v238, 19
	v_readlane_b32 s21, v238, 20
	v_readlane_b32 s22, v238, 21
	v_readlane_b32 s23, v238, 22
	v_readlane_b32 s24, v238, 23
	v_readlane_b32 s25, v238, 24
	v_readlane_b32 s26, v238, 25
	v_readlane_b32 s27, v238, 26
	v_readlane_b32 s28, v238, 27
	v_readlane_b32 s29, v238, 28
	v_readlane_b32 s30, v238, 29
	v_readlane_b32 s31, v238, 30
	s_cbranch_execz .LBB0_908
	v_mbcnt_lo_u32_b32 v1, -1, 0
	v_mbcnt_hi_u32_b32 v1, -1, v1
	v_and_b32_e32 v3, 64, v1
	v_xor_b32_e32 v2, 32, v1
	v_add_u32_e32 v3, 64, v3
	v_cmp_lt_i32_e32 vcc, v2, v3
	v_readlane_b32 s2, v238, 10
	v_readlane_b32 s36, v238, 31
	v_cndmask_b32_e32 v2, v1, v2, vcc
	v_lshlrev_b32_e32 v15, 2, v2
	v_xor_b32_e32 v2, 16, v1
	v_cmp_lt_i32_e32 vcc, v2, v3
	v_readlane_b32 s3, v238, 11
	s_lshl_b32 s2, s2, 3
	v_cndmask_b32_e32 v2, v1, v2, vcc
	v_lshlrev_b32_e32 v16, 2, v2
	v_xor_b32_e32 v2, 8, v1
	v_cmp_lt_i32_e32 vcc, v2, v3
	v_mov_b32_e32 v5, 0
	v_readlane_b32 s50, v238, 45
	v_cndmask_b32_e32 v2, v1, v2, vcc
	v_lshlrev_b32_e32 v17, 2, v2
	v_xor_b32_e32 v2, 4, v1
	v_cmp_lt_i32_e32 vcc, v2, v3
	v_readlane_b32 s51, v238, 46
	v_mov_b64_e32 v[6:7], 0x18ba5800
	v_cndmask_b32_e32 v2, v1, v2, vcc
	v_lshlrev_b32_e32 v18, 2, v2
	v_xor_b32_e32 v2, 2, v1
	v_cmp_lt_i32_e32 vcc, v2, v3
	s_ashr_i32 s3, s2, 31
	v_and_b32_e32 v12, 63, v14
	v_cndmask_b32_e32 v2, v1, v2, vcc
	v_lshlrev_b32_e32 v19, 2, v2
	v_xor_b32_e32 v2, 1, v1
	v_cmp_lt_i32_e32 vcc, v2, v3
	s_lshl_b64 s[4:5], s[2:3], 2
	s_lshl_b64 s[6:7], s[2:3], 12
	v_cndmask_b32_e32 v1, v1, v2, vcc
	v_lshlrev_b32_e32 v20, 2, v1
	v_lshlrev_b32_e32 v1, 4, v14
	v_and_b32_e32 v4, 0x3f0, v1
	v_ashrrev_i32_e32 v1, 31, v0
	v_lshlrev_b64 v[8:9], 12, v[0:1]
	v_lshlrev_b64 v[10:11], 11, v[0:1]
	v_lshl_add_u64 v[2:3], s[50:51], 0, v[4:5]
	v_lshl_add_u64 v[4:5], s[84:85], 0, v[4:5]
	v_lshl_add_u64 v[6:7], v[0:1], 2, v[6:7]
	v_lshl_or_b32 v8, v12, 4, v8
	v_lshl_or_b32 v10, v12, 3, v10
	s_lshl_b64 s[8:9], s[2:3], 11
	s_mov_b64 s[10:11], 0
	v_mov_b32_e32 v1, 0x358637bd
	s_mov_b32 s3, 0x800000
	s_movk_i32 s12, 0x7fff
	v_readlane_b32 s37, v238, 32
	v_readlane_b32 s38, v238, 33
	v_readlane_b32 s39, v238, 34
	v_readlane_b32 s40, v238, 35
	v_readlane_b32 s41, v238, 36
	v_readlane_b32 s42, v238, 37
	v_readlane_b32 s43, v238, 38
	v_readlane_b32 s44, v238, 39
	v_readlane_b32 s45, v238, 40
	v_readlane_b32 s46, v238, 41
	v_readlane_b32 s47, v238, 42
	v_readlane_b32 s48, v238, 43
	v_readlane_b32 s49, v238, 44
	global_load_dwordx4 v[200:203], v[2:3], off
	global_load_dwordx4 v[204:207], v[2:3], off offset:1024
	global_load_dwordx4 v[208:211], v[2:3], off offset:2048
	global_load_dwordx4 v[212:215], v[2:3], off offset:3072
	global_load_dwordx4 v[216:219], v[4:5], off
	global_load_dwordx4 v[220:223], v[4:5], off offset:1024
	global_load_dwordx4 v[224:227], v[4:5], off offset:2048
	global_load_dwordx4 v[228:231], v[4:5], off offset:3072
	s_waitcnt vmcnt(0)
; DI float bflo(unsigned u) { return __uint_as_float(u << 16); }
; DI float bfhi(unsigned u) { return __uint_as_float(u & 0xffff0000u); }
; DI void phase9(const Params& p) {
;     ...
;     for (int row = VBLK * 4 + w; row < T; row += VGRID * 4) {
;         f32x4 fv[4], mv[4]; float ss = 0.f;
; #pragma unroll
;         for (int i = 0; i < 4; ++i) {
;             const u32x2 u = *(const u32x2*)(F + (size_t)row * 1024 + i * 256 + lane * 4);
;             fv[i][0] = bflo(u.x); fv[i][1] = bfhi(u.x); fv[i][2] = bflo(u.y); fv[i][3] = bfhi(u.y);
;             const u32x2 um = *(const u32x2*)(MIX + (size_t)row * 1024 + i * 256 + lane * 4);
;             mv[i][0] = bflo(um.x); mv[i][1] = bfhi(um.x); mv[i][2] = bflo(um.y); mv[i][3] = bfhi(um.y);
;             ss += fv[i][0] * fv[i][0] + fv[i][1] * fv[i][1] + fv[i][2] * fv[i][2] + fv[i][3] * fv[i][3];
;         }
;         ss = wave_sum(ss);
;         const float rstd = rsqrtf(ss * (1.f / 1024.f) + NORM_EPS);
;         const float rstd1 = RSTD[row];
; #pragma unroll
;         for (int i = 0; i < 4; ++i) {
;             const f32x4 ga = *(const f32x4*)(g1 + i * 256 + lane * 4);
;             const f32x4 gb = *(const f32x4*)(g2 + i * 256 + lane * 4);
;             f32x4 xv = *(const f32x4*)(x + (size_t)row * 1024 + i * 256 + lane * 4);
; #pragma unroll
;             for (int e = 0; e < 4; ++e) { xv[e] += mv[i][e] * rstd1 * ga[e]; xv[e] += fv[i][e] * rstd * gb[e]; }
;             *(f32x4*)(p.out + (size_t)row * 1024 + i * 256 + lane * 4) = xv;
;         }
.LBB0_907:
	v_lshl_add_u64 v[34:35], s[88:89], 0, v[10:11]
	v_add_co_u32_e32 v40, vcc, 0x5ba5000, v34
	v_lshl_add_u64 v[36:37], s[88:89], 0, v[6:7]
	s_nop 0
	v_addc_co_u32_e32 v41, vcc, 0, v35, vcc
	v_lshl_add_u64 v[38:39], s[16:17], 0, v[8:9]
	global_load_dword v42, v[36:37], off
	s_nop 0
	global_load_dwordx2 v[36:37], v[40:41], off offset:2048
	global_load_dwordx2 v[44:45], v[40:41], off offset:2560
	global_load_dwordx2 v[46:47], v[40:41], off offset:3072
	global_load_dwordx2 v[48:49], v[40:41], off offset:3584
	v_add_co_u32_e32 v34, vcc, 0x9ba5000, v34
	v_lshl_add_u64 v[12:13], s[86:87], 0, v[8:9]
	s_nop 0
	v_addc_co_u32_e32 v35, vcc, 0, v35, vcc
	global_load_dwordx2 v[40:41], v[34:35], off offset:2048
	global_load_dwordx2 v[50:51], v[34:35], off offset:2560
	global_load_dwordx2 v[52:53], v[34:35], off offset:3072
	global_load_dwordx2 v[54:55], v[34:35], off offset:3584
	global_load_dwordx4 v[30:33], v[38:39], off
	global_load_dwordx4 v[80:83], v[38:39], off offset:1024
	global_load_dwordx4 v[84:87], v[38:39], off offset:2048
	global_load_dwordx4 v[88:91], v[38:39], off offset:3072
	v_add_u32_e32 v0, s2, v0
	v_lshl_add_u64 v[6:7], v[6:7], 0, s[4:5]
	v_lshl_add_u64 v[8:9], v[8:9], 0, s[6:7]
	v_lshl_add_u64 v[10:11], v[10:11], 0, s[8:9]
	s_waitcnt vmcnt(3)
	v_and_b32_e32 v35, 0xffff0000, v36
	v_and_b32_e32 v57, 0xffff0000, v44
	v_lshlrev_b32_e32 v34, 16, v36
	v_lshlrev_b32_e32 v56, 16, v44
	v_and_b32_e32 v59, 0xffff0000, v46
	v_and_b32_e32 v61, 0xffff0000, v48
	v_lshlrev_b32_e32 v62, 16, v40
	v_and_b32_e32 v63, 0xffff0000, v40
	v_mov_b32_e32 v66, v35
	v_mov_b32_e32 v67, v57
	v_lshlrev_b32_e32 v36, 16, v37
	v_lshlrev_b32_e32 v44, 16, v45
	v_lshlrev_b32_e32 v58, 16, v46
	v_lshlrev_b32_e32 v60, 16, v48
	v_lshlrev_b32_e32 v40, 16, v41
	v_and_b32_e32 v41, 0xffff0000, v41
	v_mov_b32_e32 v64, v34
	v_mov_b32_e32 v65, v56
	v_mov_b32_e32 v74, v59
	v_mov_b32_e32 v75, v61
	v_pk_mul_f32 v[62:63], v[42:43], v[62:63] op_sel_hi:[0,1]
	v_pk_mul_f32 v[66:67], v[66:67], v[66:67]
	v_and_b32_e32 v37, 0xffff0000, v37
	v_and_b32_e32 v45, 0xffff0000, v45
	v_lshlrev_b32_e32 v46, 16, v47
	v_lshlrev_b32_e32 v48, 16, v49
	v_mov_b32_e32 v68, v36
	v_mov_b32_e32 v69, v44
	v_mov_b32_e32 v72, v58
	v_mov_b32_e32 v73, v60
	v_pk_mul_f32 v[40:41], v[42:43], v[40:41] op_sel_hi:[0,1]
	v_pk_mul_f32 v[74:75], v[74:75], v[74:75]
	v_pk_fma_f32 v[22:23], v[62:63], v[200:201], v[30:31]
	v_pk_fma_f32 v[30:31], v[64:65], v[64:65], v[66:67]
	v_and_b32_e32 v47, 0xffff0000, v47
	v_and_b32_e32 v49, 0xffff0000, v49
	v_mov_b32_e32 v70, v37
	v_mov_b32_e32 v71, v45
	v_mov_b32_e32 v76, v46
	v_mov_b32_e32 v77, v48
	v_pk_fma_f32 v[24:25], v[40:41], v[202:203], v[32:33]
	v_pk_fma_f32 v[32:33], v[72:73], v[72:73], v[74:75]
	v_pk_fma_f32 v[30:31], v[68:69], v[68:69], v[30:31]
	v_mov_b32_e32 v78, v47
	v_mov_b32_e32 v79, v49
	v_pk_fma_f32 v[32:33], v[76:77], v[76:77], v[32:33]
	v_pk_fma_f32 v[30:31], v[70:71], v[70:71], v[30:31]
	v_pk_fma_f32 v[32:33], v[78:79], v[78:79], v[32:33]
	v_add_f32_e32 v21, v30, v31
	v_add_f32_e32 v21, v21, v32
	v_add_f32_e32 v21, v21, v33
	ds_bpermute_b32 v30, v15, v21
	s_waitcnt lgkmcnt(0)
	v_add_f32_e32 v21, v21, v30
	ds_bpermute_b32 v30, v16, v21
	s_waitcnt lgkmcnt(0)
	v_add_f32_e32 v21, v21, v30
	ds_bpermute_b32 v30, v17, v21
	s_waitcnt lgkmcnt(0)
	v_add_f32_e32 v21, v21, v30
	ds_bpermute_b32 v30, v18, v21
	s_waitcnt lgkmcnt(0)
	v_add_f32_e32 v21, v21, v30
	ds_bpermute_b32 v30, v19, v21
	s_waitcnt lgkmcnt(0)
	v_add_f32_e32 v21, v21, v30
	ds_bpermute_b32 v30, v20, v21
	s_waitcnt lgkmcnt(0)
	v_add_f32_e32 v21, v21, v30
	v_fmamk_f32 v21, v21, 0x3a800000, v1
	v_mul_f32_e32 v30, 0x4b800000, v21
	v_cmp_gt_f32_e32 vcc, s3, v21
	s_nop 1
	v_cndmask_b32_e32 v21, v21, v30, vcc
	v_rsq_f32_e32 v21, v21
	s_nop 0
	v_mul_f32_e32 v30, 0x45800000, v21
	v_cndmask_b32_e32 v40, v21, v30, vcc
	v_pk_mul_f32 v[30:31], v[40:41], v[34:35] op_sel_hi:[0,1]
	v_pk_mul_f32 v[32:33], v[40:41], v[36:37] op_sel_hi:[0,1]
	v_pk_fma_f32 v[22:23], v[216:217], v[30:31], v[22:23]
	v_pk_fma_f32 v[24:25], v[218:219], v[32:33], v[24:25]
	global_store_dwordx4 v[12:13], v[22:25], off
	v_lshlrev_b32_e32 v34, 16, v50
	v_and_b32_e32 v35, 0xffff0000, v50
	v_lshlrev_b32_e32 v36, 16, v51
	v_and_b32_e32 v37, 0xffff0000, v51
	v_pk_mul_f32 v[34:35], v[42:43], v[34:35] op_sel_hi:[0,1]
	v_pk_mul_f32 v[36:37], v[42:43], v[36:37] op_sel_hi:[0,1]
	v_pk_mul_f32 v[50:51], v[40:41], v[56:57] op_sel_hi:[0,1]
	v_pk_mul_f32 v[44:45], v[40:41], v[44:45] op_sel_hi:[0,1]
	v_pk_mul_f32 v[46:47], v[40:41], v[46:47] op_sel_hi:[0,1]
	v_cmp_lt_i32_e32 vcc, s12, v0
	s_or_b64 s[10:11], vcc, s[10:11]
	s_waitcnt vmcnt(3)
	v_pk_fma_f32 v[22:23], v[34:35], v[204:205], v[80:81]
	v_pk_fma_f32 v[24:25], v[36:37], v[206:207], v[82:83]
	v_pk_fma_f32 v[22:23], v[220:221], v[50:51], v[22:23]
	v_pk_fma_f32 v[24:25], v[222:223], v[44:45], v[24:25]
	global_store_dwordx4 v[12:13], v[22:25], off offset:1024
	v_lshlrev_b32_e32 v34, 16, v52
	v_and_b32_e32 v35, 0xffff0000, v52
	v_lshlrev_b32_e32 v36, 16, v53
	v_and_b32_e32 v37, 0xffff0000, v53
	v_pk_mul_f32 v[34:35], v[42:43], v[34:35] op_sel_hi:[0,1]
	v_pk_mul_f32 v[36:37], v[42:43], v[36:37] op_sel_hi:[0,1]
	v_pk_mul_f32 v[44:45], v[40:41], v[58:59] op_sel_hi:[0,1]
	s_waitcnt vmcnt(3)
	v_pk_fma_f32 v[22:23], v[34:35], v[208:209], v[84:85]
	v_pk_fma_f32 v[24:25], v[36:37], v[210:211], v[86:87]
	v_pk_fma_f32 v[22:23], v[224:225], v[44:45], v[22:23]
	v_pk_fma_f32 v[24:25], v[226:227], v[46:47], v[24:25]
	global_store_dwordx4 v[12:13], v[22:25], off offset:2048
	v_lshlrev_b32_e32 v34, 16, v54
	v_and_b32_e32 v35, 0xffff0000, v54
	v_lshlrev_b32_e32 v36, 16, v55
	v_and_b32_e32 v37, 0xffff0000, v55
	v_pk_mul_f32 v[34:35], v[42:43], v[34:35] op_sel_hi:[0,1]
	v_pk_mul_f32 v[36:37], v[42:43], v[36:37] op_sel_hi:[0,1]
	v_pk_mul_f32 v[38:39], v[40:41], v[60:61] op_sel_hi:[0,1]
	v_pk_mul_f32 v[40:41], v[40:41], v[48:49] op_sel_hi:[0,1]
	s_waitcnt vmcnt(3)
	v_pk_fma_f32 v[22:23], v[34:35], v[212:213], v[88:89]
	v_pk_fma_f32 v[24:25], v[36:37], v[214:215], v[90:91]
	v_pk_fma_f32 v[22:23], v[38:39], v[228:229], v[22:23]
	v_pk_fma_f32 v[24:25], v[40:41], v[230:231], v[24:25]
	global_store_dwordx4 v[12:13], v[22:25], off offset:3072
	s_andn2_b64 exec, exec, s[10:11]
	s_cbranch_execnz .LBB0_907
